# v14 + PREP mod-GEMV loop: prefetch next 4 weight rows, 4-deep pipelined LDS reads
# speedup vs baseline: 1.0158x; 1.0067x over previous
; #define LAS __attribute__((address_space(3)))
; DI void phase_prep(ArgsP AP, LAS unsigned char* lds) {
;     ...
;             float acc[24][2];
; #pragma unroll
;             for (int b = 0; b < 24; ++b) { acc[b][0] = 0.f; acc[b][1] = 0.f; }
;             const float* wp = adaw + ((size_t)l * 1024 + wave * 128) * 6144 + cgp * 128 + 2 * lane;
;             for (int k4 = 0; k4 < 32; ++k4) {
;                 f32x2 wv[4];
; #pragma unroll
;                 for (int kk = 0; kk < 4; ++kk) wv[kk] = *(const f32x2*)(wp + (size_t)(k4 * 4 + kk) * 6144);
; #pragma unroll
;                 for (int b = 0; b < 24; ++b) {
;                     const f32x4 cv = *(const LAS f32x4*)(cs + b * 1024 + wave * 128 + k4 * 4);
;                     acc[b][0] += cv[0] * wv[0][0] + cv[1] * wv[1][0] + cv[2] * wv[2][0] + cv[3] * wv[3][0];
;                     acc[b][1] += cv[0] * wv[0][1] + cv[1] * wv[1][1] + cv[2] * wv[2][1] + cv[3] * wv[3][1];
;                 }
;             }
.LBB0_1165:
	s_or_b64 exec, exec, s[0:1]
	s_mul_hi_i32 s0, s17, 0x2aaaaaab
	s_lshr_b32 s1, s0, 31
	s_ashr_i32 s0, s0, 3
	s_add_i32 s14, s0, s1
	s_mul_i32 s0, s14, 48
	s_sub_i32 s0, s17, s0
	s_lshl_b32 s0, s0, 7
	s_ashr_i32 s1, s0, 31
	s_mul_i32 s7, s14, 0x1800000
	s_lshl_b64 s[2:3], s[0:1], 2
	s_mul_hi_i32 s6, s14, 0x1800000
	s_add_u32 s2, s7, s2
	s_addc_u32 s3, s6, s3
	v_mov_b32_e32 v10, 0
	v_lshl_add_u64 v[12:13], v[8:9], 0, s[2:3]
	s_mov_b32 s2, 0
	v_mov_b32_e32 v11, v10
	v_mov_b32_e32 v14, v10
	v_mov_b32_e32 v15, v10
	v_mov_b32_e32 v16, v10
	v_mov_b32_e32 v17, v10
	v_mov_b32_e32 v18, v10
	v_mov_b32_e32 v19, v10
	v_mov_b32_e32 v20, v10
	v_mov_b32_e32 v21, v10
	v_mov_b32_e32 v22, v10
	v_mov_b32_e32 v23, v10
	v_mov_b32_e32 v24, v10
	v_mov_b32_e32 v25, v10
	v_mov_b32_e32 v26, v10
	v_mov_b32_e32 v27, v10
	v_mov_b32_e32 v28, v10
	v_mov_b32_e32 v29, v10
	v_mov_b32_e32 v30, v10
	v_mov_b32_e32 v31, v10
	v_mov_b32_e32 v32, v10
	v_mov_b32_e32 v33, v10
	v_mov_b32_e32 v34, v10
	v_mov_b32_e32 v35, v10
	v_mov_b32_e32 v36, v10
	v_mov_b32_e32 v37, v10
	v_mov_b32_e32 v38, v10
	v_mov_b32_e32 v39, v10
	v_mov_b32_e32 v40, v10
	v_mov_b32_e32 v41, v10
	v_mov_b32_e32 v42, v10
	v_mov_b32_e32 v43, v10
	v_mov_b32_e32 v44, v10
	v_mov_b32_e32 v45, v10
	v_mov_b32_e32 v46, v10
	v_mov_b32_e32 v47, v10
	v_mov_b32_e32 v48, v10
	v_mov_b32_e32 v49, v10
	v_mov_b32_e32 v50, v10
	v_mov_b32_e32 v51, v10
	v_mov_b32_e32 v52, v10
	v_mov_b32_e32 v53, v10
	v_mov_b32_e32 v54, v10
	v_mov_b32_e32 v55, v10
	v_mov_b32_e32 v56, v10
	v_mov_b32_e32 v57, v10
	v_mov_b32_e32 v58, v10
	v_mov_b32_e32 v59, v10
	s_waitcnt vmcnt(0) lgkmcnt(0)
	s_mov_b32 s3, 0xfffee000
	v_add_co_u32_e32 v60, vcc, s3, v12
	s_mov_b32 s3, 0xffff4000
	s_nop 0
	v_addc_co_u32_e32 v61, vcc, -1, v13, vcc
	v_add_co_u32_e32 v66, vcc, s3, v12
	global_load_dwordx2 v[60:61], v[60:61], off
	s_nop 0
	v_addc_co_u32_e32 v67, vcc, -1, v13, vcc
	global_load_dwordx2 v[70:71], v[66:67], off
	s_movk_i32 s3, 0xa000
	v_add_co_u32_e32 v66, vcc, s3, v12
	s_nop 1
	v_addc_co_u32_e32 v67, vcc, -1, v13, vcc
	global_load_dwordx2 v[72:73], v[66:67], off
	global_load_dwordx2 v[74:75], v[12:13], off
	s_barrier
.LBB0_1166:
	s_waitcnt vmcnt(0)
	v_mov_b64_e32 v[78:79], v[60:61]
	v_mov_b64_e32 v[80:81], v[70:71]
	v_mov_b64_e32 v[82:83], v[72:73]
	v_mov_b64_e32 v[84:85], v[74:75]
	s_add_i32 s3, s16, s2
	s_add_i32 s6, s3, 0x10000
	v_mov_b32_e32 v65, s3
	v_mov_b32_e32 v98, s6
	s_add_i32 s2, s2, 16
	s_mov_b64 s[18:19], 0x18000
	v_lshl_add_u64 v[12:13], v[12:13], 0, s[18:19]
	ds_read_b128 v[86:89], v65
	ds_read_b128 v[90:93], v65 offset:4096
	ds_read_b128 v[100:103], v65 offset:8192
	s_cmpk_eq_i32 s2, 0x200
	s_cbranch_scc1 .Lprep_nopf
	s_mov_b32 s3, 0xfffee000
	v_add_co_u32_e32 v60, vcc, s3, v12
	s_mov_b32 s3, 0xffff4000
	s_nop 0
	v_addc_co_u32_e32 v61, vcc, -1, v13, vcc
	v_add_co_u32_e32 v66, vcc, s3, v12
	global_load_dwordx2 v[60:61], v[60:61], off
	s_nop 0
	v_addc_co_u32_e32 v67, vcc, -1, v13, vcc
	global_load_dwordx2 v[70:71], v[66:67], off
	s_movk_i32 s3, 0xa000
	v_add_co_u32_e32 v66, vcc, s3, v12
	s_nop 1
	v_addc_co_u32_e32 v67, vcc, -1, v13, vcc
	global_load_dwordx2 v[72:73], v[66:67], off
	global_load_dwordx2 v[74:75], v[12:13], off
.Lprep_nopf:
	ds_read_b128 v[104:107], v65 offset:12288
	s_waitcnt lgkmcnt(3)
	v_pk_mul_f32 v[76:77], v[80:81], v[86:87] op_sel:[0,1]
	s_nop 0
	v_pk_fma_f32 v[66:67], v[78:79], v[86:87], v[76:77] op_sel_hi:[1,0,1]
	s_nop 0
	v_pk_fma_f32 v[66:67], v[82:83], v[88:89], v[66:67] op_sel_hi:[1,0,1]
	v_mov_b32_e32 v88, v89
	v_pk_fma_f32 v[66:67], v[84:85], v[88:89], v[66:67] op_sel_hi:[1,0,1]
	s_nop 0
	v_pk_add_f32 v[10:11], v[10:11], v[66:67]
	ds_read_b128 v[86:89], v65 offset:16384
	s_waitcnt lgkmcnt(3)
	v_pk_mul_f32 v[76:77], v[80:81], v[90:91] op_sel:[0,1]
	s_nop 0
	v_pk_fma_f32 v[66:67], v[78:79], v[90:91], v[76:77] op_sel_hi:[1,0,1]
	s_nop 0
	v_pk_fma_f32 v[66:67], v[82:83], v[92:93], v[66:67] op_sel_hi:[1,0,1]
	v_mov_b32_e32 v92, v93
	v_pk_fma_f32 v[66:67], v[84:85], v[92:93], v[66:67] op_sel_hi:[1,0,1]
	s_nop 0
	v_pk_add_f32 v[14:15], v[14:15], v[66:67]
	ds_read_b128 v[90:93], v65 offset:20480
	s_waitcnt lgkmcnt(3)
	v_pk_mul_f32 v[76:77], v[80:81], v[100:101] op_sel:[0,1]
	s_nop 0
	v_pk_fma_f32 v[66:67], v[78:79], v[100:101], v[76:77] op_sel_hi:[1,0,1]
	s_nop 0
	v_pk_fma_f32 v[66:67], v[82:83], v[102:103], v[66:67] op_sel_hi:[1,0,1]
	v_mov_b32_e32 v102, v103
	v_pk_fma_f32 v[66:67], v[84:85], v[102:103], v[66:67] op_sel_hi:[1,0,1]
	s_nop 0
	v_pk_add_f32 v[16:17], v[16:17], v[66:67]
	ds_read_b128 v[100:103], v65 offset:24576
	s_waitcnt lgkmcnt(3)
	v_pk_mul_f32 v[76:77], v[80:81], v[104:105] op_sel:[0,1]
	s_nop 0
	v_pk_fma_f32 v[66:67], v[78:79], v[104:105], v[76:77] op_sel_hi:[1,0,1]
	s_nop 0
	v_pk_fma_f32 v[66:67], v[82:83], v[106:107], v[66:67] op_sel_hi:[1,0,1]
	v_mov_b32_e32 v106, v107
	v_pk_fma_f32 v[66:67], v[84:85], v[106:107], v[66:67] op_sel_hi:[1,0,1]
	s_nop 0
	v_pk_add_f32 v[18:19], v[18:19], v[66:67]
	ds_read_b128 v[104:107], v65 offset:28672
	s_waitcnt lgkmcnt(3)
	v_pk_mul_f32 v[76:77], v[80:81], v[86:87] op_sel:[0,1]
	s_nop 0
	v_pk_fma_f32 v[66:67], v[78:79], v[86:87], v[76:77] op_sel_hi:[1,0,1]
	s_nop 0
	v_pk_fma_f32 v[66:67], v[82:83], v[88:89], v[66:67] op_sel_hi:[1,0,1]
	v_mov_b32_e32 v88, v89
	v_pk_fma_f32 v[66:67], v[84:85], v[88:89], v[66:67] op_sel_hi:[1,0,1]
	s_nop 0
	v_pk_add_f32 v[20:21], v[20:21], v[66:67]
	ds_read_b128 v[86:89], v65 offset:32768
	s_waitcnt lgkmcnt(3)
	v_pk_mul_f32 v[76:77], v[80:81], v[90:91] op_sel:[0,1]
	s_nop 0
	v_pk_fma_f32 v[66:67], v[78:79], v[90:91], v[76:77] op_sel_hi:[1,0,1]
	s_nop 0
	v_pk_fma_f32 v[66:67], v[82:83], v[92:93], v[66:67] op_sel_hi:[1,0,1]
	v_mov_b32_e32 v92, v93
	v_pk_fma_f32 v[66:67], v[84:85], v[92:93], v[66:67] op_sel_hi:[1,0,1]
	s_nop 0
	v_pk_add_f32 v[22:23], v[22:23], v[66:67]
	ds_read_b128 v[90:93], v65 offset:36864
	s_waitcnt lgkmcnt(3)
; #define LAS __attribute__((address_space(3)))
; DI void phase_prep(ArgsP AP, LAS unsigned char* lds) {
;     ...
;                 for (int b = 0; b < 24; ++b) {
;                     const f32x4 cv = *(const LAS f32x4*)(cs + b * 1024 + wave * 128 + k4 * 4);
;                     acc[b][0] += cv[0] * wv[0][0] + cv[1] * wv[1][0] + cv[2] * wv[2][0] + cv[3] * wv[3][0];
;                     acc[b][1] += cv[0] * wv[0][1] + cv[1] * wv[1][1] + cv[2] * wv[2][1] + cv[3] * wv[3][1];
;                 }
	v_pk_mul_f32 v[76:77], v[80:81], v[100:101] op_sel:[0,1]
	s_nop 0
	v_pk_fma_f32 v[66:67], v[78:79], v[100:101], v[76:77] op_sel_hi:[1,0,1]
	s_nop 0
	v_pk_fma_f32 v[66:67], v[82:83], v[102:103], v[66:67] op_sel_hi:[1,0,1]
	v_mov_b32_e32 v102, v103
	v_pk_fma_f32 v[66:67], v[84:85], v[102:103], v[66:67] op_sel_hi:[1,0,1]
	s_nop 0
	v_pk_add_f32 v[24:25], v[24:25], v[66:67]
	ds_read_b128 v[100:103], v65 offset:40960
	s_waitcnt lgkmcnt(3)
	v_pk_mul_f32 v[76:77], v[80:81], v[104:105] op_sel:[0,1]
	s_nop 0
	v_pk_fma_f32 v[66:67], v[78:79], v[104:105], v[76:77] op_sel_hi:[1,0,1]
	s_nop 0
	v_pk_fma_f32 v[66:67], v[82:83], v[106:107], v[66:67] op_sel_hi:[1,0,1]
	v_mov_b32_e32 v106, v107
	v_pk_fma_f32 v[66:67], v[84:85], v[106:107], v[66:67] op_sel_hi:[1,0,1]
	s_nop 0
	v_pk_add_f32 v[26:27], v[26:27], v[66:67]
	ds_read_b128 v[104:107], v65 offset:45056
	s_waitcnt lgkmcnt(3)
	v_pk_mul_f32 v[76:77], v[80:81], v[86:87] op_sel:[0,1]
	s_nop 0
	v_pk_fma_f32 v[66:67], v[78:79], v[86:87], v[76:77] op_sel_hi:[1,0,1]
	s_nop 0
	v_pk_fma_f32 v[66:67], v[82:83], v[88:89], v[66:67] op_sel_hi:[1,0,1]
	v_mov_b32_e32 v88, v89
	v_pk_fma_f32 v[66:67], v[84:85], v[88:89], v[66:67] op_sel_hi:[1,0,1]
	s_nop 0
	v_pk_add_f32 v[28:29], v[28:29], v[66:67]
	ds_read_b128 v[86:89], v65 offset:49152
	s_waitcnt lgkmcnt(3)
	v_pk_mul_f32 v[76:77], v[80:81], v[90:91] op_sel:[0,1]
	s_nop 0
	v_pk_fma_f32 v[66:67], v[78:79], v[90:91], v[76:77] op_sel_hi:[1,0,1]
	s_nop 0
	v_pk_fma_f32 v[66:67], v[82:83], v[92:93], v[66:67] op_sel_hi:[1,0,1]
	v_mov_b32_e32 v92, v93
	v_pk_fma_f32 v[66:67], v[84:85], v[92:93], v[66:67] op_sel_hi:[1,0,1]
	s_nop 0
	v_pk_add_f32 v[30:31], v[30:31], v[66:67]
	ds_read_b128 v[90:93], v65 offset:53248
	s_waitcnt lgkmcnt(3)
	v_pk_mul_f32 v[76:77], v[80:81], v[100:101] op_sel:[0,1]
	s_nop 0
	v_pk_fma_f32 v[66:67], v[78:79], v[100:101], v[76:77] op_sel_hi:[1,0,1]
	s_nop 0
	v_pk_fma_f32 v[66:67], v[82:83], v[102:103], v[66:67] op_sel_hi:[1,0,1]
	v_mov_b32_e32 v102, v103
	v_pk_fma_f32 v[66:67], v[84:85], v[102:103], v[66:67] op_sel_hi:[1,0,1]
	s_nop 0
	v_pk_add_f32 v[32:33], v[32:33], v[66:67]
	ds_read_b128 v[100:103], v65 offset:57344
	s_waitcnt lgkmcnt(3)
	v_pk_mul_f32 v[76:77], v[80:81], v[104:105] op_sel:[0,1]
	s_nop 0
	v_pk_fma_f32 v[66:67], v[78:79], v[104:105], v[76:77] op_sel_hi:[1,0,1]
	s_nop 0
	v_pk_fma_f32 v[66:67], v[82:83], v[106:107], v[66:67] op_sel_hi:[1,0,1]
	v_mov_b32_e32 v106, v107
	v_pk_fma_f32 v[66:67], v[84:85], v[106:107], v[66:67] op_sel_hi:[1,0,1]
	s_nop 0
	v_pk_add_f32 v[34:35], v[34:35], v[66:67]
	ds_read_b128 v[104:107], v65 offset:61440
	s_waitcnt lgkmcnt(3)
	v_pk_mul_f32 v[76:77], v[80:81], v[86:87] op_sel:[0,1]
	s_nop 0
	v_pk_fma_f32 v[66:67], v[78:79], v[86:87], v[76:77] op_sel_hi:[1,0,1]
	s_nop 0
	v_pk_fma_f32 v[66:67], v[82:83], v[88:89], v[66:67] op_sel_hi:[1,0,1]
	v_mov_b32_e32 v88, v89
	v_pk_fma_f32 v[66:67], v[84:85], v[88:89], v[66:67] op_sel_hi:[1,0,1]
	s_nop 0
	v_pk_add_f32 v[36:37], v[36:37], v[66:67]
	ds_read_b128 v[86:89], v98
	s_waitcnt lgkmcnt(3)
	v_pk_mul_f32 v[76:77], v[80:81], v[90:91] op_sel:[0,1]
	s_nop 0
	v_pk_fma_f32 v[66:67], v[78:79], v[90:91], v[76:77] op_sel_hi:[1,0,1]
	s_nop 0
	v_pk_fma_f32 v[66:67], v[82:83], v[92:93], v[66:67] op_sel_hi:[1,0,1]
	v_mov_b32_e32 v92, v93
	v_pk_fma_f32 v[66:67], v[84:85], v[92:93], v[66:67] op_sel_hi:[1,0,1]
	s_nop 0
	v_pk_add_f32 v[38:39], v[38:39], v[66:67]
	ds_read_b128 v[90:93], v98 offset:4096
	s_waitcnt lgkmcnt(3)
	v_pk_mul_f32 v[76:77], v[80:81], v[100:101] op_sel:[0,1]
	s_nop 0
	v_pk_fma_f32 v[66:67], v[78:79], v[100:101], v[76:77] op_sel_hi:[1,0,1]
	s_nop 0
	v_pk_fma_f32 v[66:67], v[82:83], v[102:103], v[66:67] op_sel_hi:[1,0,1]
	v_mov_b32_e32 v102, v103
	v_pk_fma_f32 v[66:67], v[84:85], v[102:103], v[66:67] op_sel_hi:[1,0,1]
	s_nop 0
	v_pk_add_f32 v[40:41], v[40:41], v[66:67]
	ds_read_b128 v[100:103], v98 offset:8192
	s_waitcnt lgkmcnt(3)
	v_pk_mul_f32 v[76:77], v[80:81], v[104:105] op_sel:[0,1]
	s_nop 0
	v_pk_fma_f32 v[66:67], v[78:79], v[104:105], v[76:77] op_sel_hi:[1,0,1]
	s_nop 0
	v_pk_fma_f32 v[66:67], v[82:83], v[106:107], v[66:67] op_sel_hi:[1,0,1]
	v_mov_b32_e32 v106, v107
	v_pk_fma_f32 v[66:67], v[84:85], v[106:107], v[66:67] op_sel_hi:[1,0,1]
	s_nop 0
	v_pk_add_f32 v[42:43], v[42:43], v[66:67]
	ds_read_b128 v[104:107], v98 offset:12288
	s_waitcnt lgkmcnt(3)
; #define LAS __attribute__((address_space(3)))
; DI void phase_prep(ArgsP AP, LAS unsigned char* lds) {
;     ...
;                 for (int b = 0; b < 24; ++b) {
;                     const f32x4 cv = *(const LAS f32x4*)(cs + b * 1024 + wave * 128 + k4 * 4);
;                     acc[b][0] += cv[0] * wv[0][0] + cv[1] * wv[1][0] + cv[2] * wv[2][0] + cv[3] * wv[3][0];
;                     acc[b][1] += cv[0] * wv[0][1] + cv[1] * wv[1][1] + cv[2] * wv[2][1] + cv[3] * wv[3][1];
;                 }
;             }
;             __syncthreads();
; #pragma unroll
;             for (int b = 0; b < 24; ++b) { cs[(wave * 24 + b) * 128 + 2 * lane] = acc[b][0]; cs[(wave * 24 + b) * 128 + 2 * lane + 1] = acc[b][1]; }
;             __syncthreads();
;             for (int o = tid; o < 24 * 128; o += 512) {
;                 const int b = o >> 7, c = o & 127; float sum = adab[l * 6144 + cgp * 128 + c];
; #pragma unroll
;                 for (int w = 0; w < 8; ++w) sum += cs[(w * 24 + b) * 128 + c];
;                 mod[((size_t)l * 24 + b) * 6144 + cgp * 128 + c] = sum;
	v_pk_mul_f32 v[76:77], v[80:81], v[86:87] op_sel:[0,1]
	s_nop 0
	v_pk_fma_f32 v[66:67], v[78:79], v[86:87], v[76:77] op_sel_hi:[1,0,1]
	s_nop 0
	v_pk_fma_f32 v[66:67], v[82:83], v[88:89], v[66:67] op_sel_hi:[1,0,1]
	v_mov_b32_e32 v88, v89
	v_pk_fma_f32 v[66:67], v[84:85], v[88:89], v[66:67] op_sel_hi:[1,0,1]
	s_nop 0
	v_pk_add_f32 v[44:45], v[44:45], v[66:67]
	ds_read_b128 v[86:89], v98 offset:16384
	s_waitcnt lgkmcnt(3)
	v_pk_mul_f32 v[76:77], v[80:81], v[90:91] op_sel:[0,1]
	s_nop 0
	v_pk_fma_f32 v[66:67], v[78:79], v[90:91], v[76:77] op_sel_hi:[1,0,1]
	s_nop 0
	v_pk_fma_f32 v[66:67], v[82:83], v[92:93], v[66:67] op_sel_hi:[1,0,1]
	v_mov_b32_e32 v92, v93
	v_pk_fma_f32 v[66:67], v[84:85], v[92:93], v[66:67] op_sel_hi:[1,0,1]
	s_nop 0
	v_pk_add_f32 v[46:47], v[46:47], v[66:67]
	ds_read_b128 v[90:93], v98 offset:20480
	s_waitcnt lgkmcnt(3)
	v_pk_mul_f32 v[76:77], v[80:81], v[100:101] op_sel:[0,1]
	s_nop 0
	v_pk_fma_f32 v[66:67], v[78:79], v[100:101], v[76:77] op_sel_hi:[1,0,1]
	s_nop 0
	v_pk_fma_f32 v[66:67], v[82:83], v[102:103], v[66:67] op_sel_hi:[1,0,1]
	v_mov_b32_e32 v102, v103
	v_pk_fma_f32 v[66:67], v[84:85], v[102:103], v[66:67] op_sel_hi:[1,0,1]
	s_nop 0
	v_pk_add_f32 v[48:49], v[48:49], v[66:67]
	ds_read_b128 v[100:103], v98 offset:24576
	s_waitcnt lgkmcnt(3)
	v_pk_mul_f32 v[76:77], v[80:81], v[104:105] op_sel:[0,1]
	s_nop 0
	v_pk_fma_f32 v[66:67], v[78:79], v[104:105], v[76:77] op_sel_hi:[1,0,1]
	s_nop 0
	v_pk_fma_f32 v[66:67], v[82:83], v[106:107], v[66:67] op_sel_hi:[1,0,1]
	v_mov_b32_e32 v106, v107
	v_pk_fma_f32 v[66:67], v[84:85], v[106:107], v[66:67] op_sel_hi:[1,0,1]
	s_nop 0
	v_pk_add_f32 v[50:51], v[50:51], v[66:67]
	ds_read_b128 v[104:107], v98 offset:28672
	s_waitcnt lgkmcnt(3)
	v_pk_mul_f32 v[76:77], v[80:81], v[86:87] op_sel:[0,1]
	s_nop 0
	v_pk_fma_f32 v[66:67], v[78:79], v[86:87], v[76:77] op_sel_hi:[1,0,1]
	s_nop 0
	v_pk_fma_f32 v[66:67], v[82:83], v[88:89], v[66:67] op_sel_hi:[1,0,1]
	v_mov_b32_e32 v88, v89
	v_pk_fma_f32 v[66:67], v[84:85], v[88:89], v[66:67] op_sel_hi:[1,0,1]
	s_nop 0
	v_pk_add_f32 v[52:53], v[52:53], v[66:67]
	s_waitcnt lgkmcnt(2)
	v_pk_mul_f32 v[76:77], v[80:81], v[90:91] op_sel:[0,1]
	s_nop 0
	v_pk_fma_f32 v[66:67], v[78:79], v[90:91], v[76:77] op_sel_hi:[1,0,1]
	s_nop 0
	v_pk_fma_f32 v[66:67], v[82:83], v[92:93], v[66:67] op_sel_hi:[1,0,1]
	v_mov_b32_e32 v92, v93
	v_pk_fma_f32 v[66:67], v[84:85], v[92:93], v[66:67] op_sel_hi:[1,0,1]
	s_nop 0
	v_pk_add_f32 v[54:55], v[54:55], v[66:67]
	s_waitcnt lgkmcnt(1)
	v_pk_mul_f32 v[76:77], v[80:81], v[100:101] op_sel:[0,1]
	s_nop 0
	v_pk_fma_f32 v[66:67], v[78:79], v[100:101], v[76:77] op_sel_hi:[1,0,1]
	s_nop 0
	v_pk_fma_f32 v[66:67], v[82:83], v[102:103], v[66:67] op_sel_hi:[1,0,1]
	v_mov_b32_e32 v102, v103
	v_pk_fma_f32 v[66:67], v[84:85], v[102:103], v[66:67] op_sel_hi:[1,0,1]
	s_nop 0
	v_pk_add_f32 v[56:57], v[56:57], v[66:67]
	s_waitcnt lgkmcnt(0)
	v_pk_mul_f32 v[76:77], v[80:81], v[104:105] op_sel:[0,1]
	s_nop 0
	v_pk_fma_f32 v[66:67], v[78:79], v[104:105], v[76:77] op_sel_hi:[1,0,1]
	s_nop 0
	v_pk_fma_f32 v[66:67], v[82:83], v[106:107], v[66:67] op_sel_hi:[1,0,1]
	v_mov_b32_e32 v106, v107
	v_pk_fma_f32 v[66:67], v[84:85], v[106:107], v[66:67] op_sel_hi:[1,0,1]
	s_nop 0
	v_pk_add_f32 v[58:59], v[58:59], v[66:67]
	s_cmpk_lg_i32 s2, 0x200
	s_cbranch_scc1 .LBB0_1166
	s_barrier
	ds_write2st64_b64 v7, v[10:11], v[14:15] offset1:1
	ds_write2st64_b64 v7, v[16:17], v[18:19] offset0:2 offset1:3
	ds_write2st64_b64 v7, v[20:21], v[22:23] offset0:4 offset1:5
	ds_write2st64_b64 v7, v[24:25], v[26:27] offset0:6 offset1:7
	ds_write2st64_b64 v7, v[28:29], v[30:31] offset0:8 offset1:9
	ds_write2st64_b64 v7, v[32:33], v[34:35] offset0:10 offset1:11
	ds_write2st64_b64 v7, v[36:37], v[38:39] offset0:12 offset1:13
	ds_write2st64_b64 v7, v[40:41], v[42:43] offset0:14 offset1:15
	ds_write2st64_b64 v7, v[44:45], v[46:47] offset0:16 offset1:17
	ds_write2st64_b64 v7, v[48:49], v[50:51] offset0:18 offset1:19
	ds_write2st64_b64 v7, v[52:53], v[54:55] offset0:20 offset1:21
	ds_write2st64_b64 v7, v[56:57], v[58:59] offset0:22 offset1:23
	s_waitcnt lgkmcnt(0)
	s_barrier
	s_and_saveexec_b64 s[2:3], s[42:43]
	s_cbranch_execz .LBB0_1159
	s_mul_i32 s6, s14, 0x1800
	s_add_i32 s6, s6, s0
	v_or_b32_e32 v10, s6, v63
	v_ashrrev_i32_e32 v11, 31, v10
	s_mul_hi_i32 s15, s14, 24
	s_mul_i32 s14, s14, 24
	v_lshl_add_u64 v[10:11], v[10:11], 2, s[50:51]
	v_lshl_add_u64 v[12:13], s[0:1], 2, v[0:1]
	s_mov_b64 s[0:1], 0
	v_mov_b32_e32 v14, v2
